# FFN1 GEMM only: per-block s_setprio flips removed, one static s_setprio 1 for waves 4-7 for the phase
# speedup vs baseline: 1.0099x; 1.0099x over previous
; #define PG8_WAIT_V(n) asm volatile("s_waitcnt vmcnt(" #n ")" ::: "memory")
;     __host__ __device__ bool next(int i, Unit& u) const {
;         const long L = (long)i * G + c; if (L >= nwg) return false;
;         int wgid = (int)L; { const int q = nwg / NXCD, r = nwg % NXCD, xcd = wgid % NXCD, off = wgid / NXCD; wgid = (xcd < r ? xcd * (q + 1) : r * (q + 1) + (xcd - r) * q) + off; }
;         const int nig = WGM * nN, gid = wgid / nig, fm = gid * WGM, gsz = (nM - fm) < WGM ? (nM - fm) : WGM;
;         u.pm = fm + ((wgid % nig) % gsz); u.pn = (wgid % nig) / gsz; return true;
; template <class Epi, class Sched, bool ALIGN_EPI = false, bool SP2 = false>
; __device__ __forceinline__ void gemm_phase(PG8_LAS unsigned char* lds, const Gemm g, const Sched& S, const Epi& E) {
;     const int tid = opaque_tid(), wid = __builtin_amdgcn_readfirstlane(tid >> 6), lane = tid & 63, wr = wid >> 2, wc = wid & 3, fr = lane & 15, fq = lane >> 4;
;     const int K = g.K, nt = K / BK;
;     unsigned voffA[2], voffB[2];
; #pragma unroll
;     for (int i = 0; i < 2; ++i) { int R, C; stage_rc(tid * 16 + i * 8192, R, C); const int Rb = Epi::PERM ? ((R & ~31) + perm32(R & 31)) : R;
;         voffA[i] = (unsigned)(R * K + C) * 2u; voffB[i] = (unsigned)(Rb * K + C) * 2u; }
;     const size_t kstep = (size_t)(BK * 2);
;     const size_t hstep = (size_t)HALF * K * 2;
;     const size_t tstep = 2 * hstep;
;     const unsigned ldsw = (unsigned)wid * 1024u;
;     const int aoff = lds_byte(wr * 64 + fr, fq * 8), boff = lds_byte(wc * 32 + fr, fq * 8);
;     ...
;     Unit cur, nxt; int ui = 0;
;     if (!S.next(0, cur)) return;
;     f32x4 acc[2][2][4][2];
; #pragma unroll
;     for (int a = 0; a < 2; ++a)
; #pragma unroll
;         for (int b = 0; b < 2; ++b)
; #pragma unroll
;             for (int m = 0; m < 4; ++m)
; #pragma unroll
;                 for (int n = 0; n < 2; ++n) acc[a][b][m][n] = (f32x4){0.f, 0.f, 0.f, 0.f};
;     bf16x8 At[4][2], B0[2][2], B1[2][2];
;     const char* cA = (const char*)g.A + (size_t)cur.pm * tstep; const char* cB = (const char*)g.Bt + (size_t)cur.pn * tstep;
;     S.a_ready(cur);
;     if constexpr (SP2) {
;         PG8_STAGE(PG8_SB(0, 0), cB, voffB); PG8_STAGE(PG8_SB(0, 1), cB + hstep, voffB); PG8_STAGE(PG8_SA(0, 0), cA, voffA); PG8_STAGE(PG8_SA(0, 1), cA + hstep, voffA);
;         if (wr == 1) PG8_BAR;
;         PG8_WAIT_V(2); PG8_BAR;
.LBB0_92:
	s_movk_i32 s0, 0x400
	s_waitcnt lgkmcnt(0)
	s_barrier
	v_readfirstlane_b32 s101, v162
	s_nop 3
	s_lshr_b32 s101, s101, 6
	s_cmp_ge_u32 s101, 4
	s_cbranch_scc0 .Lprio_done_ffn1
	s_setprio 1
.Lprio_done_ffn1:
	s_ashr_i32 s1, s10, 31
	s_lshr_b32 s1, s1, 24
	s_add_i32 s1, s10, s1
	s_ashr_i32 s10, s1, 8
	s_mov_b32 s24, s67
	s_lshl_b32 s4, s10, 7
	v_mov_b32_e32 v20, v162
	s_cmp_ge_i32 s24, s4
	v_readfirstlane_b32 s5, v20
	s_cbranch_scc1 .LBB0_114
	v_lshlrev_b32_e32 v0, 4, v20
	v_add_u32_e32 v2, 0x2000, v0
	v_ashrrev_i32_e32 v3, 31, v2
	v_lshrrev_b32_e32 v3, 22, v3
	v_add_u32_e32 v3, v2, v3
	v_ashrrev_i32_e32 v3, 10, v3
	v_mul_i32_i24_e32 v4, 0x400, v3
	v_sub_u32_e32 v2, v2, v4
	v_lshrrev_b32_e32 v4, 4, v2
	s_ashr_i32 s12, s5, 6
	s_ashr_i32 s1, s0, 31
	v_bitop3_b32 v2, v4, v2, 32 bitop3:0x6c
	s_ashr_i32 s13, s5, 8
	s_lshl_b64 s[6:7], s[0:1], 8
	s_lshl_b64 s[8:9], s[0:1], 9
	s_lshl_b32 s25, s12, 10
	v_ashrrev_i32_e32 v4, 31, v2
	s_add_u32 s26, s2, 0x19100000
	v_lshrrev_b32_e32 v4, 26, v4
	s_addc_u32 s27, s3, 0
	s_mul_i32 s11, s23, 0xb00000
	v_add_u32_e32 v4, v2, v4
	v_lshlrev_b32_e32 v6, 3, v3
	s_add_u32 s11, s2, s11
	v_ashrrev_i32_e32 v5, 6, v4
	v_and_b32_e32 v6, -16, v6
	v_lshlrev_b32_e32 v3, 5, v3
	s_addc_u32 s14, s3, 0
	v_add_u32_e32 v6, v5, v6
	v_and_b32_e32 v14, 32, v3
	v_and_b32_e32 v3, 0xc0, v4
	s_add_u32 s28, s11, 0x1d00000
	v_and_b32_e32 v5, 3, v5
	s_mov_b32 s11, 0x7fffffe0
	v_lshrrev_b32_e32 v7, 2, v6
	v_lshlrev_b32_e32 v8, 1, v6
	v_sub_u32_e32 v2, v2, v3
	v_and_or_b32 v5, v6, s11, v5
	v_and_b32_e32 v7, 4, v7
	v_and_b32_e32 v8, 24, v8
	v_ashrrev_i16_sdwa v2, v165, sext(v2) dst_sel:DWORD dst_unused:UNUSED_PAD src0_sel:DWORD src1_sel:BYTE_0
	v_or3_b32 v5, v5, v7, v8
	v_bfe_i32 v15, v2, 0, 16
	v_mul_lo_u32 v5, v5, s0
	v_add_u32_e32 v2, v14, v15
	v_mul_lo_u32 v16, v6, s0
	v_add_lshl_u32 v130, v5, v2, 1
	v_add_lshl_u32 v132, v2, v16, 1
	v_bfe_i32 v2, v20, 27, 1
	v_lshrrev_b32_e32 v2, 22, v2
	v_add_u32_e32 v2, v0, v2
	v_and_b32_e32 v2, 0xfffffc00, v2
	v_sub_u32_e32 v0, v0, v2
	v_ashrrev_i32_e32 v3, 31, v20
	v_lshrrev_b32_e32 v2, 4, v0
	v_lshrrev_b32_e32 v3, 26, v3
	v_bitop3_b32 v2, v2, v0, 32 bitop3:0x6c
	v_ashrrev_i32_e32 v0, 31, v0
	v_add_u32_e32 v3, v20, v3
	v_lshrrev_b32_e32 v0, 26, v0
	v_ashrrev_i32_e32 v3, 6, v3
	v_add_u32_e32 v0, v2, v0
	v_lshlrev_b32_e32 v4, 3, v3
	v_ashrrev_i32_e32 v0, 6, v0
	v_and_b32_e32 v4, -16, v4
	s_addc_u32 s29, s14, 0
	v_add_u32_e32 v4, v0, v4
	v_and_b32_e32 v5, 3, v0
	s_ashr_i32 s31, s24, 31
	v_and_or_b32 v5, v4, s11, v5
	s_lshr_b32 s11, s31, 29
	s_add_i32 s11, s24, s11
	v_mul_i32_i24_e32 v0, 64, v0
	s_lshl_b32 s30, s10, 4
	s_ashr_i32 s14, s11, 3
	s_and_b32 s11, s11, -8
	v_lshrrev_b32_e32 v6, 2, v4
	v_lshlrev_b32_e32 v7, 1, v4
	v_sub_u32_e32 v0, v2, v0
	s_sub_i32 s11, s24, s11
	s_or_b32 s34, s30, 1
	v_and_b32_e32 v6, 4, v6
	v_and_b32_e32 v7, 24, v7
	v_lshlrev_b32_e32 v3, 5, v3
	v_ashrrev_i16_sdwa v0, v165, sext(v0) dst_sel:DWORD dst_unused:UNUSED_PAD src0_sel:DWORD src1_sel:BYTE_0
	s_cmp_lt_i32 s11, 0
	v_or3_b32 v5, v5, v6, v7
	v_and_b32_e32 v17, 32, v3
	v_bfe_i32 v18, v0, 0, 16
	s_cselect_b32 s15, s34, s30
	s_lshl_b32 s35, s10, 2
	v_mul_lo_u32 v5, v5, s0
	v_add_u32_e32 v2, v17, v18
	v_mul_lo_u32 v19, v4, s0
	s_abs_i32 s37, s35
	v_add_lshl_u32 v0, v5, v2, 1
	v_add_lshl_u32 v134, v2, v19, 1
	v_cvt_f32_u32_e32 v2, s37
	s_mul_i32 s11, s15, s11
	s_sub_i32 s15, 0, s37
	s_add_i32 s11, s11, s14
	v_rcp_iflag_f32_e32 v2, v2
	s_ashr_i32 s14, s11, 31
	s_bfe_i32 s36, s10, 0x1001d
	s_xor_b32 s10, s14, s36
	v_mul_f32_e32 v2, 0x4f7ffffe, v2
	v_cvt_u32_f32_e32 v2, v2
	s_abs_i32 s14, s11
	s_mov_b32 s62, s23
	v_mov_b32_e32 v131, v1
	v_readfirstlane_b32 s38, v2
	s_mul_i32 s15, s15, s38
	s_mul_hi_u32 s15, s38, s15
	s_add_i32 s38, s38, s15
	s_mul_hi_u32 s15, s14, s38
	s_mul_i32 s16, s15, s37
	s_sub_i32 s14, s14, s16
	s_add_i32 s16, s15, 1
	s_sub_i32 s17, s14, s37
	s_cmp_ge_u32 s14, s37
	s_cselect_b32 s15, s16, s15
	s_cselect_b32 s14, s17, s14
	s_add_i32 s16, s15, 1
	s_cmp_ge_u32 s14, s37
	s_cselect_b32 s14, s16, s15
	s_xor_b32 s14, s14, s10
	s_sub_i32 s10, s14, s10
	s_lshl_b32 s14, s10, 2
	s_sub_i32 s15, 0x80, s14
	s_min_i32 s15, s15, 4
	s_abs_i32 s17, s15
	v_cvt_f32_u32_e32 v2, s17
	s_sub_i32 s18, 0, s17
	s_mul_i32 s10, s10, s35
	s_sub_i32 s10, s11, s10
	v_rcp_iflag_f32_e32 v2, v2
	s_abs_i32 s16, s10
	s_xor_b32 s11, s10, s15
	s_ashr_i32 s11, s11, 31
	v_mul_f32_e32 v2, 0x4f7ffffe, v2
	v_cvt_u32_f32_e32 v2, v2
	v_mov_b32_e32 v135, v1
	v_mov_b32_e32 v133, v1
	v_readfirstlane_b32 s19, v2
	s_mul_i32 s18, s18, s19
	s_mul_hi_u32 s18, s19, s18
	s_add_i32 s19, s19, s18
	s_mul_hi_u32 s18, s16, s19
	s_mul_i32 s19, s18, s17
	s_sub_i32 s16, s16, s19
	s_add_i32 s19, s18, 1
	s_sub_i32 s20, s16, s17
	s_cmp_ge_u32 s16, s17
	s_cselect_b32 s18, s19, s18
	s_cselect_b32 s16, s20, s16
	s_add_i32 s19, s18, 1
	s_cmp_ge_u32 s16, s17
	s_cselect_b32 s16, s19, s18
	s_xor_b32 s16, s16, s11
	s_sub_i32 s50, s16, s11
	s_mul_i32 s11, s50, s15
	s_sub_i32 s10, s10, s11
	s_add_i32 s51, s10, s14
	s_ashr_i32 s10, s51, 31
	s_mul_i32 s10, s8, s10
	s_mul_hi_u32 s11, s8, s51
	s_add_i32 s14, s11, s10
	s_lshr_b64 s[10:11], s[0:1], 23
	s_mul_i32 s11, s10, s51
	s_add_i32 s14, s14, s11
	s_ashr_i32 s11, s50, 31
	s_mul_i32 s11, s8, s11
	s_mul_hi_u32 s16, s8, s50
	s_add_i32 s11, s16, s11
	s_mul_i32 s10, s10, s50
	s_add_i32 s11, s11, s10
	s_mul_i32 s10, s8, s50
	s_add_u32 s20, s28, s10
	s_addc_u32 s21, s29, s11
	s_add_i32 s39, s25, 0
	s_add_i32 m0, s39, 0x10000
	s_mul_i32 s15, s8, s51
	global_load_lds_dwordx4 v0, s[20:21]
	s_add_i32 m0, s39, 0x12000
	s_add_u32 s10, s20, s6
	global_load_lds_dwordx4 v130, s[20:21]
	s_addc_u32 s11, s21, s7
	s_add_i32 m0, s39, 0x14000
	v_lshl_add_u64 v[6:7], s[10:11], 0, v[0:1]
	global_load_lds_dwordx4 v0, s[10:11]
	s_add_i32 m0, s39, 0x16000
	s_add_u32 s22, s26, s15
	s_addc_u32 s23, s27, s14
	s_add_i32 s40, s39, 0x2000
	v_lshl_add_u64 v[8:9], s[10:11], 0, v[130:131]
	global_load_lds_dwordx4 v130, s[10:11]
	s_mov_b32 m0, s39
	s_add_u32 s10, s22, s6
	global_load_lds_dwordx4 v134, s[22:23]
	s_mov_b32 m0, s40
	s_addc_u32 s11, s23, s7
	s_add_i32 s41, s39, 0x4000
	global_load_lds_dwordx4 v132, s[22:23]
	s_mov_b32 m0, s41
	s_add_i32 s42, s39, 0x6000
	global_load_lds_dwordx4 v134, s[10:11]
	s_mov_b32 m0, s42
	s_cmp_eq_u32 s13, 1
	global_load_lds_dwordx4 v132, s[10:11]
	v_lshl_add_u64 v[2:3], s[20:21], 0, v[0:1]
	v_lshl_add_u64 v[4:5], s[20:21], 0, v[130:131]
	v_lshl_add_u64 v[10:11], s[22:23], 0, v[134:135]
	v_lshl_add_u64 v[12:13], s[22:23], 0, v[132:133]
	s_cselect_b64 s[10:11], -1, 0
	s_cmp_lg_u32 s13, 1
	s_cbranch_scc1 .LBB0_95
	s_barrier

; #define PG8_STAGE(bufoff, gbase, voff) do { _Pragma("unroll") for (int _i = 0; _i < 2; ++_i) \
;         __builtin_amdgcn_global_load_lds((const unsigned*)((const char*)(gbase) + (voff)[_i]), (PG8_LAS unsigned*)(lds + (bufoff) + ldsw + _i * 8192), 16, 0, 0); } while (0)
; #define PG8_LDA(dst, b, h) do { _Pragma("unroll") for (int m = 0; m < 4; ++m) _Pragma("unroll") for (int k = 0; k < 2; ++k) dst[m][k] = *(const PG8_LAS bf16x8*)(lds + PG8_SA(b, h) + aoff + m * 2048 + k * 1024); } while (0)
; #define PG8_LDB(dst, b, h) do { _Pragma("unroll") for (int n = 0; n < 2; ++n) _Pragma("unroll") for (int k = 0; k < 2; ++k) dst[n][k] = *(const PG8_LAS bf16x8*)(lds + PG8_SB(b, h) + boff + n * 2048 + k * 1024); } while (0)
; #define PG8_WAIT_V(n) asm volatile("s_waitcnt vmcnt(" #n ")" ::: "memory")
; #define PG8_WAIT_L(n) asm volatile("s_waitcnt lgkmcnt(" #n ")" ::: "memory")
; #define PG8_BAR __builtin_amdgcn_s_barrier()
; #define PG8_SCHED __builtin_amdgcn_sched_barrier(0)
; template <class Epi, class Sched, bool ALIGN_EPI = false, bool SP2 = false>
; __device__ __forceinline__ void gemm_phase(PG8_LAS unsigned char* lds, const Gemm g, const Sched& S, const Epi& E) {
;     ...
;         const char* nA = has_next ? (const char*)g.A + (size_t)nxt.pm * tstep : cA; const char* nB = has_next ? (const char*)g.Bt + (size_t)nxt.pn * tstep : cB;
;         for (int t = 0; t < nt; t += 2) {
;             const bool last = (t == nt - 2);
;             const char* a1 = cA + (size_t)(t + 1) * kstep;
;             const char* a2 = last ? nA : cA + (size_t)(t + 2) * kstep; const char* b2 = last ? nB : cB + (size_t)(t + 2) * kstep;
;             const char* a3 = a2 + kstep; const char* b3 = b2 + kstep;
;             if (last && has_next) S.a_ready(nxt);
;             if constexpr (SP2) {
;             PG8_LDB(B0, 0, 0); PG8_LDB(B1, 0, 1); PG8_SCHED; PG8_LDA(At, 0, 0); PG8_STAGE(PG8_SA(1, 1), a1 + hstep, voffA);
;             PG8_WAIT_V(8); PG8_WAIT_L(0); PG8_BAR; PG8_MMA(0, 0, At, B0); PG8_MMA(0, 1, At, B1); PG8_BAR; PG8_SCHED;
;             PG8_LDA(At, 0, 1); PG8_STAGE(PG8_SB(0, 0), b2, voffB); PG8_STAGE(PG8_SB(0, 1), b2 + hstep, voffB); PG8_STAGE(PG8_SA(0, 0), a2, voffA);
;             PG8_WAIT_V(8); PG8_WAIT_L(0); PG8_BAR; PG8_MMA(1, 0, At, B0); PG8_MMA(1, 1, At, B1); PG8_BAR; PG8_SCHED;
.LBB0_106:
	s_add_i32 s55, s22, 2
	s_add_u32 s56, s20, 0x80
	s_addc_u32 s23, s21, 0
	s_add_i32 s58, 0, 0x10000
	s_cmp_eq_u32 s46, s22
	s_cselect_b32 s23, s3, s23
	s_cselect_b32 s22, s2, s56
	v_add_u32_e32 v144, s58, v152
	s_cselect_b32 s57, s19, s54
	s_cselect_b32 s56, s18, s53
	s_add_i32 s59, 0, 0x14000
	ds_read_b128 v[140:143], v144
	ds_read_b128 v[148:151], v144 offset:1024
	ds_read_b128 v[156:159], v144 offset:2048
	ds_read_b128 v[174:177], v144 offset:3072
	v_add_u32_e32 v144, s59, v152
	ds_read_b128 v[178:181], v144
	ds_read_b128 v[182:185], v144 offset:1024
	ds_read_b128 v[186:189], v144 offset:2048
	ds_read_b128 v[190:193], v144 offset:3072
	v_lshl_add_u64 v[144:145], s[20:21], 0, v[138:139]
	s_add_i32 m0, s39, 0xc000
	ds_read_b128 v[194:197], v155
	ds_read_b128 v[198:201], v155 offset:1024
	ds_read_b128 v[202:205], v155 offset:2048
	ds_read_b128 v[206:209], v155 offset:3072
	ds_read_b128 v[210:213], v155 offset:4096
	ds_read_b128 v[214:217], v155 offset:5120
	ds_read_b128 v[218:221], v155 offset:6144
	ds_read_b128 v[222:225], v155 offset:7168
	global_load_lds_dwordx4 v[144:145], off
	v_lshl_add_u64 v[144:145], s[20:21], 0, v[136:137]
	s_add_i32 m0, s39, 0xe000
	s_nop 0
	global_load_lds_dwordx4 v[144:145], off
	s_waitcnt vmcnt(8)
	s_waitcnt lgkmcnt(0)
	s_barrier
	s_waitcnt lgkmcnt(0)
	v_mfma_f32_16x16x32_bf16 v[122:125], v[140:143], v[194:197], v[122:125]
	v_mfma_f32_16x16x32_bf16 v[114:117], v[156:159], v[194:197], v[114:117]
	v_mfma_f32_16x16x32_bf16 v[106:109], v[140:143], v[202:205], v[106:109]
	v_mfma_f32_16x16x32_bf16 v[98:101], v[156:159], v[202:205], v[98:101]
	v_mfma_f32_16x16x32_bf16 v[90:93], v[140:143], v[210:213], v[90:93]
	v_mfma_f32_16x16x32_bf16 v[82:85], v[156:159], v[210:213], v[82:85]
	v_mfma_f32_16x16x32_bf16 v[74:77], v[140:143], v[218:221], v[74:77]
	v_mfma_f32_16x16x32_bf16 v[66:69], v[156:159], v[218:221], v[66:69]
	v_mfma_f32_16x16x32_bf16 v[122:125], v[148:151], v[198:201], v[122:125]
	v_mfma_f32_16x16x32_bf16 v[114:117], v[174:177], v[198:201], v[114:117]
	v_mfma_f32_16x16x32_bf16 v[106:109], v[148:151], v[206:209], v[106:109]
	v_mfma_f32_16x16x32_bf16 v[98:101], v[174:177], v[206:209], v[98:101]
	v_mfma_f32_16x16x32_bf16 v[90:93], v[148:151], v[214:217], v[90:93]
	v_mfma_f32_16x16x32_bf16 v[82:85], v[174:177], v[214:217], v[82:85]
	v_mfma_f32_16x16x32_bf16 v[74:77], v[148:151], v[222:225], v[74:77]
	v_mfma_f32_16x16x32_bf16 v[66:69], v[174:177], v[222:225], v[66:69]
	v_mfma_f32_16x16x32_bf16 v[126:129], v[178:181], v[194:197], v[126:129]
	v_mfma_f32_16x16x32_bf16 v[118:121], v[186:189], v[194:197], v[118:121]
	v_mfma_f32_16x16x32_bf16 v[110:113], v[178:181], v[202:205], v[110:113]
	v_mfma_f32_16x16x32_bf16 v[102:105], v[186:189], v[202:205], v[102:105]
	v_mfma_f32_16x16x32_bf16 v[94:97], v[178:181], v[210:213], v[94:97]
	v_mfma_f32_16x16x32_bf16 v[86:89], v[186:189], v[210:213], v[86:89]
	v_mfma_f32_16x16x32_bf16 v[78:81], v[178:181], v[218:221], v[78:81]
	v_mfma_f32_16x16x32_bf16 v[70:73], v[186:189], v[218:221], v[70:73]
	v_mfma_f32_16x16x32_bf16 v[126:129], v[182:185], v[198:201], v[126:129]
	v_mfma_f32_16x16x32_bf16 v[118:121], v[190:193], v[198:201], v[118:121]
	v_mfma_f32_16x16x32_bf16 v[110:113], v[182:185], v[206:209], v[110:113]
	v_mfma_f32_16x16x32_bf16 v[102:105], v[190:193], v[206:209], v[102:105]
	v_mfma_f32_16x16x32_bf16 v[94:97], v[182:185], v[214:217], v[94:97]
	v_mfma_f32_16x16x32_bf16 v[86:89], v[190:193], v[214:217], v[86:89]
	v_mfma_f32_16x16x32_bf16 v[78:81], v[182:185], v[222:225], v[78:81]
	v_mfma_f32_16x16x32_bf16 v[70:73], v[190:193], v[222:225], v[70:73]
	s_barrier
	s_add_i32 s58, s58, s25
	v_lshl_add_u64 v[144:145], s[56:57], 0, v[0:1]
	s_mov_b32 m0, s58
	ds_read_b128 v[194:197], v155 offset:16384
	ds_read_b128 v[198:201], v155 offset:17408
	ds_read_b128 v[202:205], v155 offset:18432
	ds_read_b128 v[206:209], v155 offset:19456
	ds_read_b128 v[210:213], v155 offset:20480
	ds_read_b128 v[214:217], v155 offset:21504
	ds_read_b128 v[218:221], v155 offset:22528
	ds_read_b128 v[222:225], v155 offset:23552
	global_load_lds_dwordx4 v[144:145], off
	s_add_i32 m0, s58, 0x2000
	v_lshl_add_u64 v[160:161], s[56:57], 0, v[130:131]
	s_add_u32 s56, s56, s6
	s_addc_u32 s57, s57, s7
	s_add_i32 s58, s59, s25
	global_load_lds_dwordx4 v[160:161], off
	v_lshl_add_u64 v[226:227], s[56:57], 0, v[0:1]
	s_mov_b32 m0, s58
	v_lshl_add_u64 v[228:229], s[56:57], 0, v[130:131]
	global_load_lds_dwordx4 v[226:227], off
	s_add_i32 m0, s58, 0x2000
	v_lshl_add_u64 v[230:231], s[22:23], 0, v[134:135]
	global_load_lds_dwordx4 v[228:229], off
	s_mov_b32 m0, s39
	v_lshl_add_u64 v[232:233], s[22:23], 0, v[132:133]
	global_load_lds_dwordx4 v[230:231], off
	s_mov_b32 m0, s40
	s_nop 0
	global_load_lds_dwordx4 v[232:233], off
	s_waitcnt vmcnt(8)
	s_waitcnt lgkmcnt(0)
	s_barrier
; #define PG8_STAGE(bufoff, gbase, voff) do { _Pragma("unroll") for (int _i = 0; _i < 2; ++_i) \
;         __builtin_amdgcn_global_load_lds((const unsigned*)((const char*)(gbase) + (voff)[_i]), (PG8_LAS unsigned*)(lds + (bufoff) + ldsw + _i * 8192), 16, 0, 0); } while (0)
; #define PG8_LDA(dst, b, h) do { _Pragma("unroll") for (int m = 0; m < 4; ++m) _Pragma("unroll") for (int k = 0; k < 2; ++k) dst[m][k] = *(const PG8_LAS bf16x8*)(lds + PG8_SA(b, h) + aoff + m * 2048 + k * 1024); } while (0)
; #define PG8_LDB(dst, b, h) do { _Pragma("unroll") for (int n = 0; n < 2; ++n) _Pragma("unroll") for (int k = 0; k < 2; ++k) dst[n][k] = *(const PG8_LAS bf16x8*)(lds + PG8_SB(b, h) + boff + n * 2048 + k * 1024); } while (0)
; #define PG8_MMA(ai, bj, At, Bt) do { __builtin_amdgcn_s_setprio(1); _Pragma("unroll") for (int m = 0; m < 4; ++m) _Pragma("unroll") for (int n = 0; n < 2; ++n) _Pragma("unroll") for (int k = 0; k < 2; ++k) \
;         acc[ai][bj][m][n] = __builtin_amdgcn_mfma_f32_16x16x32_bf16(Bt[n][k], At[m][k], acc[ai][bj][m][n], 0, 0, 0); __builtin_amdgcn_s_setprio(0); } while (0)
; #define PG8_WAIT_V(n) asm volatile("s_waitcnt vmcnt(" #n ")" ::: "memory")
; #define PG8_WAIT_L(n) asm volatile("s_waitcnt lgkmcnt(" #n ")" ::: "memory")
; #define PG8_BAR __builtin_amdgcn_s_barrier()
; #define PG8_SCHED __builtin_amdgcn_sched_barrier(0)
; template <class Epi, class Sched, bool ALIGN_EPI = false, bool SP2 = false>
; __device__ __forceinline__ void gemm_phase(PG8_LAS unsigned char* lds, const Gemm g, const Sched& S, const Epi& E) {
;     ...
;             PG8_WAIT_V(8); PG8_WAIT_L(0); PG8_BAR; PG8_MMA(1, 0, At, B0); PG8_MMA(1, 1, At, B1); PG8_BAR; PG8_SCHED;
;             PG8_LDB(B0, 1, 0); PG8_LDB(B1, 1, 1); PG8_SCHED; PG8_LDA(At, 1, 0); PG8_STAGE(PG8_SA(0, 1), a2 + hstep, voffA);
;             PG8_WAIT_V(8); PG8_WAIT_L(0); PG8_BAR; PG8_MMA(0, 0, At, B0); PG8_MMA(0, 1, At, B1); PG8_BAR; PG8_SCHED;
	s_waitcnt lgkmcnt(0)
	v_mfma_f32_16x16x32_bf16 v[58:61], v[140:143], v[194:197], v[58:61]
	v_mfma_f32_16x16x32_bf16 v[50:53], v[156:159], v[194:197], v[50:53]
	v_mfma_f32_16x16x32_bf16 v[42:45], v[140:143], v[202:205], v[42:45]
	v_mfma_f32_16x16x32_bf16 v[34:37], v[156:159], v[202:205], v[34:37]
	v_mfma_f32_16x16x32_bf16 v[26:29], v[140:143], v[210:213], v[26:29]
	v_mfma_f32_16x16x32_bf16 v[18:21], v[156:159], v[210:213], v[18:21]
	v_mfma_f32_16x16x32_bf16 v[10:13], v[140:143], v[218:221], v[10:13]
	v_mfma_f32_16x16x32_bf16 v[6:9], v[156:159], v[218:221], v[6:9]
	v_mfma_f32_16x16x32_bf16 v[58:61], v[148:151], v[198:201], v[58:61]
	v_mfma_f32_16x16x32_bf16 v[50:53], v[174:177], v[198:201], v[50:53]
	v_mfma_f32_16x16x32_bf16 v[42:45], v[148:151], v[206:209], v[42:45]
	v_mfma_f32_16x16x32_bf16 v[34:37], v[174:177], v[206:209], v[34:37]
	v_mfma_f32_16x16x32_bf16 v[26:29], v[148:151], v[214:217], v[26:29]
	v_mfma_f32_16x16x32_bf16 v[18:21], v[174:177], v[214:217], v[18:21]
	v_mfma_f32_16x16x32_bf16 v[10:13], v[148:151], v[222:225], v[10:13]
	v_mfma_f32_16x16x32_bf16 v[6:9], v[174:177], v[222:225], v[6:9]
	v_mfma_f32_16x16x32_bf16 v[62:65], v[178:181], v[194:197], v[62:65]
	v_mfma_f32_16x16x32_bf16 v[54:57], v[186:189], v[194:197], v[54:57]
	v_mfma_f32_16x16x32_bf16 v[46:49], v[178:181], v[202:205], v[46:49]
	v_mfma_f32_16x16x32_bf16 v[38:41], v[186:189], v[202:205], v[38:41]
	v_mfma_f32_16x16x32_bf16 v[30:33], v[178:181], v[210:213], v[30:33]
	v_mfma_f32_16x16x32_bf16 v[22:25], v[186:189], v[210:213], v[22:25]
	v_mfma_f32_16x16x32_bf16 v[14:17], v[178:181], v[218:221], v[14:17]
	v_mfma_f32_16x16x32_bf16 v[2:5], v[186:189], v[218:221], v[2:5]
	v_mfma_f32_16x16x32_bf16 v[62:65], v[182:185], v[198:201], v[62:65]
	v_mfma_f32_16x16x32_bf16 v[54:57], v[190:193], v[198:201], v[54:57]
	v_mfma_f32_16x16x32_bf16 v[46:49], v[182:185], v[206:209], v[46:49]
	v_mfma_f32_16x16x32_bf16 v[38:41], v[190:193], v[206:209], v[38:41]
	v_mfma_f32_16x16x32_bf16 v[30:33], v[182:185], v[214:217], v[30:33]
	v_mfma_f32_16x16x32_bf16 v[22:25], v[190:193], v[214:217], v[22:25]
	v_mfma_f32_16x16x32_bf16 v[14:17], v[182:185], v[222:225], v[14:17]
	v_mfma_f32_16x16x32_bf16 v[2:5], v[190:193], v[222:225], v[2:5]
	s_barrier
	s_add_i32 s56, 0, 0x18000
	s_add_i32 s57, 0, 0x1c000
	v_add_u32_e32 v174, s56, v152
	v_add_u32_e32 v190, s57, v152
	ds_read_b128 v[140:143], v174
	ds_read_b128 v[148:151], v174 offset:1024
	ds_read_b128 v[156:159], v174 offset:2048
	ds_read_b128 v[174:177], v174 offset:3072
	ds_read_b128 v[178:181], v190
	ds_read_b128 v[182:185], v190 offset:1024
	ds_read_b128 v[186:189], v190 offset:2048
	ds_read_b128 v[190:193], v190 offset:3072
	s_add_u32 s22, s22, s6
	s_addc_u32 s23, s23, s7
	s_mov_b32 m0, s41
	v_lshl_add_u64 v[234:235], s[22:23], 0, v[134:135]
	ds_read_b128 v[194:197], v155 offset:32768
	ds_read_b128 v[198:201], v155 offset:33792
	ds_read_b128 v[202:205], v155 offset:34816
	ds_read_b128 v[206:209], v155 offset:35840
	ds_read_b128 v[210:213], v155 offset:36864
	ds_read_b128 v[214:217], v155 offset:37888
	ds_read_b128 v[218:221], v155 offset:38912
	ds_read_b128 v[222:225], v155 offset:39936
	global_load_lds_dwordx4 v[234:235], off
	v_lshl_add_u64 v[234:235], s[22:23], 0, v[132:133]
	s_mov_b32 m0, s42
	s_nop 0
	global_load_lds_dwordx4 v[234:235], off
	s_waitcnt vmcnt(8)
	s_waitcnt lgkmcnt(0)
	s_barrier
	s_waitcnt lgkmcnt(0)
	v_mfma_f32_16x16x32_bf16 v[122:125], v[140:143], v[194:197], v[122:125]
	v_mfma_f32_16x16x32_bf16 v[114:117], v[156:159], v[194:197], v[114:117]
	v_mfma_f32_16x16x32_bf16 v[106:109], v[140:143], v[202:205], v[106:109]
	v_mfma_f32_16x16x32_bf16 v[98:101], v[156:159], v[202:205], v[98:101]
	v_mfma_f32_16x16x32_bf16 v[90:93], v[140:143], v[210:213], v[90:93]
	v_mfma_f32_16x16x32_bf16 v[82:85], v[156:159], v[210:213], v[82:85]
	v_mfma_f32_16x16x32_bf16 v[74:77], v[140:143], v[218:221], v[74:77]
	v_mfma_f32_16x16x32_bf16 v[66:69], v[156:159], v[218:221], v[66:69]
	v_mfma_f32_16x16x32_bf16 v[122:125], v[148:151], v[198:201], v[122:125]
	v_mfma_f32_16x16x32_bf16 v[114:117], v[174:177], v[198:201], v[114:117]
	v_mfma_f32_16x16x32_bf16 v[106:109], v[148:151], v[206:209], v[106:109]
	v_mfma_f32_16x16x32_bf16 v[98:101], v[174:177], v[206:209], v[98:101]
	v_mfma_f32_16x16x32_bf16 v[90:93], v[148:151], v[214:217], v[90:93]
	v_mfma_f32_16x16x32_bf16 v[82:85], v[174:177], v[214:217], v[82:85]
	v_mfma_f32_16x16x32_bf16 v[74:77], v[148:151], v[222:225], v[74:77]
	v_mfma_f32_16x16x32_bf16 v[66:69], v[174:177], v[222:225], v[66:69]
	v_mfma_f32_16x16x32_bf16 v[126:129], v[178:181], v[194:197], v[126:129]
	v_mfma_f32_16x16x32_bf16 v[118:121], v[186:189], v[194:197], v[118:121]
	v_mfma_f32_16x16x32_bf16 v[110:113], v[178:181], v[202:205], v[110:113]
	v_mfma_f32_16x16x32_bf16 v[102:105], v[186:189], v[202:205], v[102:105]
	v_mfma_f32_16x16x32_bf16 v[94:97], v[178:181], v[210:213], v[94:97]
	v_mfma_f32_16x16x32_bf16 v[86:89], v[186:189], v[210:213], v[86:89]
	v_mfma_f32_16x16x32_bf16 v[78:81], v[178:181], v[218:221], v[78:81]
	v_mfma_f32_16x16x32_bf16 v[70:73], v[186:189], v[218:221], v[70:73]
	v_mfma_f32_16x16x32_bf16 v[126:129], v[182:185], v[198:201], v[126:129]
	v_mfma_f32_16x16x32_bf16 v[118:121], v[190:193], v[198:201], v[118:121]
	v_mfma_f32_16x16x32_bf16 v[110:113], v[182:185], v[206:209], v[110:113]
	v_mfma_f32_16x16x32_bf16 v[102:105], v[190:193], v[206:209], v[102:105]
	v_mfma_f32_16x16x32_bf16 v[94:97], v[182:185], v[214:217], v[94:97]
	v_mfma_f32_16x16x32_bf16 v[86:89], v[190:193], v[214:217], v[86:89]
	v_mfma_f32_16x16x32_bf16 v[78:81], v[182:185], v[222:225], v[78:81]
	v_mfma_f32_16x16x32_bf16 v[70:73], v[190:193], v[222:225], v[70:73]
	s_barrier
; #define PG8_STAGE(bufoff, gbase, voff) do { _Pragma("unroll") for (int _i = 0; _i < 2; ++_i) \
;         __builtin_amdgcn_global_load_lds((const unsigned*)((const char*)(gbase) + (voff)[_i]), (PG8_LAS unsigned*)(lds + (bufoff) + ldsw + _i * 8192), 16, 0, 0); } while (0)
; #define PG8_LDA(dst, b, h) do { _Pragma("unroll") for (int m = 0; m < 4; ++m) _Pragma("unroll") for (int k = 0; k < 2; ++k) dst[m][k] = *(const PG8_LAS bf16x8*)(lds + PG8_SA(b, h) + aoff + m * 2048 + k * 1024); } while (0)
; #define PG8_MMA(ai, bj, At, Bt) do { __builtin_amdgcn_s_setprio(1); _Pragma("unroll") for (int m = 0; m < 4; ++m) _Pragma("unroll") for (int n = 0; n < 2; ++n) _Pragma("unroll") for (int k = 0; k < 2; ++k) \
;         acc[ai][bj][m][n] = __builtin_amdgcn_mfma_f32_16x16x32_bf16(Bt[n][k], At[m][k], acc[ai][bj][m][n], 0, 0, 0); __builtin_amdgcn_s_setprio(0); } while (0)
; #define PG8_WAIT_V(n) asm volatile("s_waitcnt vmcnt(" #n ")" ::: "memory")
; #define PG8_WAIT_L(n) asm volatile("s_waitcnt lgkmcnt(" #n ")" ::: "memory")
; #define PG8_BAR __builtin_amdgcn_s_barrier()
; #define PG8_SCHED __builtin_amdgcn_sched_barrier(0)
; template <class Epi, class Sched, bool ALIGN_EPI = false, bool SP2 = false>
; __device__ __forceinline__ void gemm_phase(PG8_LAS unsigned char* lds, const Gemm g, const Sched& S, const Epi& E) {
;     ...
;         for (int t = 0; t < nt; t += 2) {
;             const bool last = (t == nt - 2);
;             const char* a1 = cA + (size_t)(t + 1) * kstep;
;             const char* a2 = last ? nA : cA + (size_t)(t + 2) * kstep; const char* b2 = last ? nB : cB + (size_t)(t + 2) * kstep;
;             const char* a3 = a2 + kstep; const char* b3 = b2 + kstep;
;     ...
;             PG8_LDA(At, 1, 1); PG8_STAGE(PG8_SB(1, 0), b3, voffB); PG8_STAGE(PG8_SB(1, 1), b3 + hstep, voffB); PG8_STAGE(PG8_SA(1, 0), a3, voffA);
;             PG8_WAIT_V(8); PG8_WAIT_L(0); PG8_BAR; PG8_MMA(1, 0, At, B0); PG8_MMA(1, 1, At, B1); PG8_BAR; PG8_SCHED;
	s_add_i32 s22, s56, s25
	v_lshl_add_u64 v[144:145], v[144:145], 0, s[80:81]
	s_mov_b32 m0, s22
	ds_read_b128 v[194:197], v155 offset:49152
	ds_read_b128 v[198:201], v155 offset:50176
	ds_read_b128 v[202:205], v155 offset:51200
	ds_read_b128 v[206:209], v155 offset:52224
	ds_read_b128 v[210:213], v155 offset:53248
	ds_read_b128 v[214:217], v155 offset:54272
	ds_read_b128 v[218:221], v155 offset:55296
	ds_read_b128 v[222:225], v155 offset:56320
	global_load_lds_dwordx4 v[144:145], off
	v_lshl_add_u64 v[144:145], v[160:161], 0, s[80:81]
	s_add_i32 m0, s22, 0x2000
	s_add_i32 s22, s57, s25
	global_load_lds_dwordx4 v[144:145], off
	v_lshl_add_u64 v[144:145], v[226:227], 0, s[80:81]
	s_mov_b32 m0, s22
	s_nop 0
	global_load_lds_dwordx4 v[144:145], off
	v_lshl_add_u64 v[144:145], v[228:229], 0, s[80:81]
	s_add_i32 m0, s22, 0x2000
	s_nop 0
	global_load_lds_dwordx4 v[144:145], off
	v_lshl_add_u64 v[144:145], v[230:231], 0, s[80:81]
	s_mov_b32 m0, s44
	s_nop 0
	global_load_lds_dwordx4 v[144:145], off
	v_lshl_add_u64 v[144:145], v[232:233], 0, s[80:81]
	s_mov_b32 m0, s45
	s_nop 0
	global_load_lds_dwordx4 v[144:145], off
	s_waitcnt vmcnt(8)
	s_waitcnt lgkmcnt(0)
	s_barrier
	s_waitcnt lgkmcnt(0)
	v_mfma_f32_16x16x32_bf16 v[58:61], v[140:143], v[194:197], v[58:61]
	v_mfma_f32_16x16x32_bf16 v[50:53], v[156:159], v[194:197], v[50:53]
	v_mfma_f32_16x16x32_bf16 v[42:45], v[140:143], v[202:205], v[42:45]
	v_mfma_f32_16x16x32_bf16 v[34:37], v[156:159], v[202:205], v[34:37]
	v_mfma_f32_16x16x32_bf16 v[26:29], v[140:143], v[210:213], v[26:29]
	v_mfma_f32_16x16x32_bf16 v[18:21], v[156:159], v[210:213], v[18:21]
	v_mfma_f32_16x16x32_bf16 v[10:13], v[140:143], v[218:221], v[10:13]
	v_mfma_f32_16x16x32_bf16 v[6:9], v[156:159], v[218:221], v[6:9]
	v_mfma_f32_16x16x32_bf16 v[58:61], v[148:151], v[198:201], v[58:61]
	v_mfma_f32_16x16x32_bf16 v[50:53], v[174:177], v[198:201], v[50:53]
	v_mfma_f32_16x16x32_bf16 v[42:45], v[148:151], v[206:209], v[42:45]
	v_mfma_f32_16x16x32_bf16 v[34:37], v[174:177], v[206:209], v[34:37]
	v_mfma_f32_16x16x32_bf16 v[26:29], v[148:151], v[214:217], v[26:29]
	v_mfma_f32_16x16x32_bf16 v[18:21], v[174:177], v[214:217], v[18:21]
	v_mfma_f32_16x16x32_bf16 v[10:13], v[148:151], v[222:225], v[10:13]
	v_mfma_f32_16x16x32_bf16 v[6:9], v[174:177], v[222:225], v[6:9]
	v_mfma_f32_16x16x32_bf16 v[62:65], v[178:181], v[194:197], v[62:65]
	v_mfma_f32_16x16x32_bf16 v[54:57], v[186:189], v[194:197], v[54:57]
	v_mfma_f32_16x16x32_bf16 v[46:49], v[178:181], v[202:205], v[46:49]
	v_mfma_f32_16x16x32_bf16 v[38:41], v[186:189], v[202:205], v[38:41]
	v_mfma_f32_16x16x32_bf16 v[30:33], v[178:181], v[210:213], v[30:33]
	v_mfma_f32_16x16x32_bf16 v[22:25], v[186:189], v[210:213], v[22:25]
	v_mfma_f32_16x16x32_bf16 v[14:17], v[178:181], v[218:221], v[14:17]
	v_mfma_f32_16x16x32_bf16 v[2:5], v[186:189], v[218:221], v[2:5]
	v_mfma_f32_16x16x32_bf16 v[62:65], v[182:185], v[198:201], v[62:65]
	v_mfma_f32_16x16x32_bf16 v[54:57], v[190:193], v[198:201], v[54:57]
	v_mfma_f32_16x16x32_bf16 v[46:49], v[182:185], v[206:209], v[46:49]
	v_mfma_f32_16x16x32_bf16 v[38:41], v[190:193], v[206:209], v[38:41]
	v_mfma_f32_16x16x32_bf16 v[30:33], v[182:185], v[214:217], v[30:33]
	v_mfma_f32_16x16x32_bf16 v[22:25], v[190:193], v[214:217], v[22:25]
	v_mfma_f32_16x16x32_bf16 v[14:17], v[182:185], v[222:225], v[14:17]
	v_mfma_f32_16x16x32_bf16 v[2:5], v[190:193], v[222:225], v[2:5]
	s_barrier
	s_add_u32 s53, s53, 0x100
	s_addc_u32 s54, s54, 0
	s_add_u32 s20, s20, 0x100
	s_addc_u32 s21, s21, 0
	s_cmp_ge_i32 s55, s43
	s_mov_b32 s22, s55
	s_cbranch_scc0 .LBB0_106
	v_readlane_b32 s56, v239, 36
	v_readlane_b32 s57, v239, 37

; #define PG8_WAIT_V(n) asm volatile("s_waitcnt vmcnt(" #n ")" ::: "memory")
; #define PG8_BAR __builtin_amdgcn_s_barrier()
; template <class Epi, class Sched, bool ALIGN_EPI = false, bool SP2 = false>
; __device__ __forceinline__ void gemm_phase(PG8_LAS unsigned char* lds, const Gemm g, const Sched& S, const Epi& E) {
;     ...
;     PG8_WAIT_V(0);
;     if constexpr (!ALIGN_EPI) { if (wr == 0) PG8_BAR; }
;     PG8_BAR;
; __device__ __forceinline__ void xcd_barrier(const XcdBarrier& b) {
;     asm volatile("s_waitcnt vmcnt(0)" ::: "memory");
;     __syncthreads();
;     if (threadIdx.x == 0) {
;         unsigned* bar = b.bar;
;         __builtin_amdgcn_s_waitcnt(0);
;         unsigned nloc = b.st[0], nx = b.st[1];
;         if (nloc == 0u) { xcd_barrier_complete(bar, b.x, nloc, nx); b.st[0] = nloc; b.st[1] = nx; }
.LBB0_114:
	s_setprio 0
	s_waitcnt vmcnt(0)
	s_waitcnt vmcnt(0)
	s_barrier
	s_and_saveexec_b64 s[0:1], s[72:73]
	v_readlane_b32 s14, v239, 38
	s_mov_b64 s[10:11], s[60:61]
	v_readlane_b32 s15, v239, 39
	s_cbranch_execz .LBB0_166
	v_readlane_b32 s2, v240, 43
	s_waitcnt vmcnt(0) expcnt(0) lgkmcnt(0)
	s_nop 0
	v_mov_b32_e32 v0, s2
	ds_read_b32 v3, v0
	v_readlane_b32 s2, v240, 44
	s_waitcnt lgkmcnt(0)
	v_cmp_ne_u32_e32 vcc, 0, v3
	v_mov_b32_e32 v0, s2
	ds_read_b32 v2, v0
	s_cbranch_vccnz .LBB0_130
	s_mov_b32 s8, 1
	s_branch .LBB0_118
